# rwkv_out rewritten by hand: one wave per row, four channels per lane with 16/8-byte loads and stores, 16-lane DPP head reductions, next row prefetched
# speedup vs baseline: 1.0119x; 1.0065x over previous
.LBB0_258:
	s_andn2_b64 vcc, exec, s[24:25]
	s_cbranch_vccnz .LBB0_2065
	v_readlane_b32 s2, v250, 24
	s_cmp_lt_i32 s2, 2
	s_mov_b64 s[24:25], -1
	s_cbranch_scc1 .LBB0_1280
	v_readlane_b32 s2, v250, 24
	s_cmp_gt_i32 s2, 2
	s_cbranch_scc0 .LBB0_275
	s_mov_b64 s[24:25], exec
	s_waitcnt vmcnt(0)
	v_and_b32_e32 v9, 63, v232
	v_lshlrev_b32_e32 v10, 4, v9
	v_lshlrev_b32_e32 v11, 3, v9
	v_readfirstlane_b32 s5, v232
	s_lshl_b32 s4, s30, 3
	s_lshr_b32 s5, s5, 6
	s_add_i32 s4, s4, s5
	s_cmp_lt_u32 s4, s82
	s_cbranch_scc0 .Lro_done
	v_readlane_b32 s6, v250, 60
	s_lshl_b32 s6, s6, 2
	v_add_u32_e32 v8, s6, v10
	v_readlane_b32 s12, v251, 22
	v_readlane_b32 s13, v251, 23
	v_readlane_b32 s14, v251, 0
	v_readlane_b32 s15, v251, 1
	v_readlane_b32 s16, v251, 18
	v_readlane_b32 s17, v251, 19
	s_nop 4
	global_load_dwordx4 v[12:15], v8, s[12:13]
	global_load_dwordx4 v[16:19], v8, s[14:15]
	global_load_dwordx4 v[20:23], v8, s[16:17]
	s_lshl_b32 s6, s4, 11
	s_add_u32 s8, s92, s6
	s_addc_u32 s9, s93, 0
	s_add_u32 s10, s8, 0x13800000
	s_addc_u32 s11, s9, 0
	global_load_dwordx4 v[24:27], v10, s[10:11]
	global_load_dwordx4 v[28:31], v10, s[10:11] offset:1024
	s_lshr_b32 s7, s6, 1
	s_add_u32 s12, s92, s7
	s_addc_u32 s13, s93, 0
	s_add_u32 s12, s12, 0xfc00000
	s_addc_u32 s13, s13, 0
	global_load_dwordx2 v[34:35], v11, s[12:13]
	global_load_dwordx2 v[36:37], v11, s[12:13] offset:512
	s_lshr_b32 s7, s6, 2
	s_add_u32 s14, s92, s7
	s_addc_u32 s15, s93, 0
	s_add_u32 s16, s14, 0x11e00000
	s_addc_u32 s17, s15, 0
	global_load_dwordx2 v[32:33], v11, s[16:17]
	s_add_u32 s16, s14, 0x12680000
	s_addc_u32 s17, s15, 0
	global_load_dwordx2 v[38:39], v11, s[16:17]
	s_add_u32 s16, s14, 0x12f00000
	s_addc_u32 s17, s15, 0
	global_load_dwordx2 v[40:41], v11, s[16:17]
.Lro_loop:
	s_add_i32 s5, s4, 0x800
	s_cmp_lt_u32 s5, s82
	s_cbranch_scc0 .Lro_last_a
	s_lshl_b32 s6, s5, 11
	s_add_u32 s8, s92, s6
	s_addc_u32 s9, s93, 0
	s_add_u32 s10, s8, 0x13800000
	s_addc_u32 s11, s9, 0
	global_load_dwordx4 v[44:47], v10, s[10:11]
	global_load_dwordx4 v[48:51], v10, s[10:11] offset:1024
	s_lshr_b32 s7, s6, 1
	s_add_u32 s12, s92, s7
	s_addc_u32 s13, s93, 0
	s_add_u32 s12, s12, 0xfc00000
	s_addc_u32 s13, s13, 0
	global_load_dwordx2 v[54:55], v11, s[12:13]
	global_load_dwordx2 v[56:57], v11, s[12:13] offset:512
	s_lshr_b32 s7, s6, 2
	s_add_u32 s14, s92, s7
	s_addc_u32 s15, s93, 0
	s_add_u32 s16, s14, 0x11e00000
	s_addc_u32 s17, s15, 0
	global_load_dwordx2 v[52:53], v11, s[16:17]
	s_add_u32 s16, s14, 0x12680000
	s_addc_u32 s17, s15, 0
	global_load_dwordx2 v[58:59], v11, s[16:17]
	s_add_u32 s16, s14, 0x12f00000
	s_addc_u32 s17, s15, 0
	global_load_dwordx2 v[60:61], v11, s[16:17]
	s_waitcnt vmcnt(7)
	v_pk_add_f32 v[62:63], v[24:25], v[28:29]
	v_pk_add_f32 v[64:65], v[26:27], v[30:31]
	v_pk_add_f32 v[66:67], v[62:63], v[64:65]
	v_add_f32_e32 v66, v66, v67
	v_lshlrev_b32_e32 v68, 16, v34
	v_and_b32_e32 v69, 0xffff0000, v34
	v_add_f32_dpp v66, v66, v66 quad_perm:[1,0,3,2] row_mask:0xf bank_mask:0xf bound_ctrl:1
	v_lshlrev_b32_e32 v70, 16, v35
	v_and_b32_e32 v71, 0xffff0000, v35
	v_add_f32_dpp v66, v66, v66 quad_perm:[2,3,0,1] row_mask:0xf bank_mask:0xf bound_ctrl:1
	v_lshlrev_b32_e32 v72, 16, v36
	v_and_b32_e32 v73, 0xffff0000, v36
	v_add_f32_dpp v66, v66, v66 row_half_mirror row_mask:0xf bank_mask:0xf bound_ctrl:1
	v_lshlrev_b32_e32 v74, 16, v37
	v_and_b32_e32 v75, 0xffff0000, v37
	v_add_f32_dpp v66, v66, v66 row_ror:8 row_mask:0xf bank_mask:0xf bound_ctrl:1
	v_pk_add_f32 v[68:69], v[68:69], v[72:73]
	v_pk_add_f32 v[70:71], v[70:71], v[74:75]
	v_lshlrev_b32_e32 v72, 16, v32
	v_and_b32_e32 v73, 0xffff0000, v32
	v_lshlrev_b32_e32 v74, 16, v33
	v_and_b32_e32 v75, 0xffff0000, v33
	v_pk_mul_f32 v[68:69], v[68:69], v[72:73]
	v_pk_mul_f32 v[70:71], v[70:71], v[74:75]
	v_pk_mul_f32 v[68:69], v[20:21], v[68:69]
	v_pk_mul_f32 v[70:71], v[22:23], v[70:71]
	v_pk_add_f32 v[68:69], v[68:69], v[70:71]
	v_add_f32_e32 v68, v68, v69
	v_fmac_f32_e32 v62, 0xbc800000, v66
	v_fmac_f32_e32 v63, 0xbc800000, v66
	v_add_f32_dpp v68, v68, v68 quad_perm:[1,0,3,2] row_mask:0xf bank_mask:0xf bound_ctrl:1
	v_fmac_f32_e32 v64, 0xbc800000, v66
	v_fmac_f32_e32 v65, 0xbc800000, v66
	v_add_f32_dpp v68, v68, v68 quad_perm:[2,3,0,1] row_mask:0xf bank_mask:0xf bound_ctrl:1
	v_pk_mul_f32 v[76:77], v[62:63], v[62:63]
	v_pk_fma_f32 v[76:77], v[64:65], v[64:65], v[76:77]
	v_add_f32_dpp v68, v68, v68 row_half_mirror row_mask:0xf bank_mask:0xf bound_ctrl:1
	s_nop 0
	s_nop 0
	v_add_f32_dpp v68, v68, v68 row_ror:8 row_mask:0xf bank_mask:0xf bound_ctrl:1
	v_add_f32_e32 v76, v76, v77
	v_lshlrev_b32_e32 v72, 16, v38
	v_and_b32_e32 v73, 0xffff0000, v38
	v_add_f32_dpp v76, v76, v76 quad_perm:[1,0,3,2] row_mask:0xf bank_mask:0xf bound_ctrl:1
	v_lshlrev_b32_e32 v74, 16, v39
	v_and_b32_e32 v75, 0xffff0000, v39
	v_add_f32_dpp v76, v76, v76 quad_perm:[2,3,0,1] row_mask:0xf bank_mask:0xf bound_ctrl:1
	v_lshlrev_b32_e32 v78, 16, v40
	v_and_b32_e32 v79, 0xffff0000, v40
	v_add_f32_dpp v76, v76, v76 row_half_mirror row_mask:0xf bank_mask:0xf bound_ctrl:1
	v_lshlrev_b32_e32 v80, 16, v41
	v_and_b32_e32 v81, 0xffff0000, v41
	v_add_f32_dpp v76, v76, v76 row_ror:8 row_mask:0xf bank_mask:0xf bound_ctrl:1
	s_mov_b32 s6, 0x3a27c5ac
	v_mov_b32_e32 v77, s6
	v_fmac_f32_e32 v77, 0x3c800000, v76
	v_rsq_f32_e32 v77, v77
	s_nop 0
	v_mul_f32_e32 v62, v62, v77
	v_mul_f32_e32 v63, v63, v77
	v_mul_f32_e32 v64, v64, v77
	v_mul_f32_e32 v65, v65, v77
	v_mul_f32_e32 v62, v12, v62
	v_mul_f32_e32 v63, v13, v63
	v_mul_f32_e32 v64, v14, v64
	v_mul_f32_e32 v65, v15, v65
	v_pk_add_f32 v[62:63], v[16:17], v[62:63]
	v_pk_add_f32 v[64:65], v[18:19], v[64:65]
	v_fmac_f32_e32 v62, v68, v72
	v_fmac_f32_e32 v63, v68, v73
	v_fmac_f32_e32 v64, v68, v74
	v_fmac_f32_e32 v65, v68, v75
	v_pk_mul_f32 v[62:63], v[62:63], v[78:79]
	v_pk_mul_f32 v[64:65], v[64:65], v[80:81]
	v_cvt_pk_bf16_f32 v62, v62, v63
	v_cvt_pk_bf16_f32 v63, v64, v65
	s_lshl_b32 s6, s4, 11
	s_add_u32 s8, s92, s6
	s_addc_u32 s9, s93, 0
	s_add_u32 s8, s8, 0x1e00600
	s_addc_u32 s9, s9, 0
	global_store_dwordx2 v11, v[62:63], s[8:9]
	s_add_i32 s4, s5, 0x800
	s_cmp_lt_u32 s4, s82
	s_cbranch_scc0 .Lro_last_b
	s_lshl_b32 s6, s4, 11
	s_add_u32 s8, s92, s6
	s_addc_u32 s9, s93, 0
	s_add_u32 s10, s8, 0x13800000
	s_addc_u32 s11, s9, 0
	global_load_dwordx4 v[24:27], v10, s[10:11]
	global_load_dwordx4 v[28:31], v10, s[10:11] offset:1024
	s_lshr_b32 s7, s6, 1
	s_add_u32 s12, s92, s7
	s_addc_u32 s13, s93, 0
	s_add_u32 s12, s12, 0xfc00000
	s_addc_u32 s13, s13, 0
	global_load_dwordx2 v[34:35], v11, s[12:13]
	global_load_dwordx2 v[36:37], v11, s[12:13] offset:512
	s_lshr_b32 s7, s6, 2
	s_add_u32 s14, s92, s7
	s_addc_u32 s15, s93, 0
	s_add_u32 s16, s14, 0x11e00000
	s_addc_u32 s17, s15, 0
	global_load_dwordx2 v[32:33], v11, s[16:17]
	s_add_u32 s16, s14, 0x12680000
	s_addc_u32 s17, s15, 0
	global_load_dwordx2 v[38:39], v11, s[16:17]
	s_add_u32 s16, s14, 0x12f00000
	s_addc_u32 s17, s15, 0
	global_load_dwordx2 v[40:41], v11, s[16:17]
	s_waitcnt vmcnt(7)
	v_pk_add_f32 v[62:63], v[44:45], v[48:49]
	v_pk_add_f32 v[64:65], v[46:47], v[50:51]
	v_pk_add_f32 v[66:67], v[62:63], v[64:65]
	v_add_f32_e32 v66, v66, v67
	v_lshlrev_b32_e32 v68, 16, v54
	v_and_b32_e32 v69, 0xffff0000, v54
	v_add_f32_dpp v66, v66, v66 quad_perm:[1,0,3,2] row_mask:0xf bank_mask:0xf bound_ctrl:1
	v_lshlrev_b32_e32 v70, 16, v55
	v_and_b32_e32 v71, 0xffff0000, v55
	v_add_f32_dpp v66, v66, v66 quad_perm:[2,3,0,1] row_mask:0xf bank_mask:0xf bound_ctrl:1
	v_lshlrev_b32_e32 v72, 16, v56
	v_and_b32_e32 v73, 0xffff0000, v56
	v_add_f32_dpp v66, v66, v66 row_half_mirror row_mask:0xf bank_mask:0xf bound_ctrl:1
	v_lshlrev_b32_e32 v74, 16, v57
	v_and_b32_e32 v75, 0xffff0000, v57
	v_add_f32_dpp v66, v66, v66 row_ror:8 row_mask:0xf bank_mask:0xf bound_ctrl:1
	v_pk_add_f32 v[68:69], v[68:69], v[72:73]
	v_pk_add_f32 v[70:71], v[70:71], v[74:75]
	v_lshlrev_b32_e32 v72, 16, v52
	v_and_b32_e32 v73, 0xffff0000, v52
	v_lshlrev_b32_e32 v74, 16, v53
	v_and_b32_e32 v75, 0xffff0000, v53
	v_pk_mul_f32 v[68:69], v[68:69], v[72:73]
	v_pk_mul_f32 v[70:71], v[70:71], v[74:75]
	v_pk_mul_f32 v[68:69], v[20:21], v[68:69]
	v_pk_mul_f32 v[70:71], v[22:23], v[70:71]
	v_pk_add_f32 v[68:69], v[68:69], v[70:71]
	v_add_f32_e32 v68, v68, v69
	v_fmac_f32_e32 v62, 0xbc800000, v66
	v_fmac_f32_e32 v63, 0xbc800000, v66
	v_add_f32_dpp v68, v68, v68 quad_perm:[1,0,3,2] row_mask:0xf bank_mask:0xf bound_ctrl:1
	v_fmac_f32_e32 v64, 0xbc800000, v66
	v_fmac_f32_e32 v65, 0xbc800000, v66
	v_add_f32_dpp v68, v68, v68 quad_perm:[2,3,0,1] row_mask:0xf bank_mask:0xf bound_ctrl:1
	v_pk_mul_f32 v[76:77], v[62:63], v[62:63]
	v_pk_fma_f32 v[76:77], v[64:65], v[64:65], v[76:77]
	v_add_f32_dpp v68, v68, v68 row_half_mirror row_mask:0xf bank_mask:0xf bound_ctrl:1
	s_nop 0
	s_nop 0
	v_add_f32_dpp v68, v68, v68 row_ror:8 row_mask:0xf bank_mask:0xf bound_ctrl:1
	v_add_f32_e32 v76, v76, v77
	v_lshlrev_b32_e32 v72, 16, v58
	v_and_b32_e32 v73, 0xffff0000, v58
	v_add_f32_dpp v76, v76, v76 quad_perm:[1,0,3,2] row_mask:0xf bank_mask:0xf bound_ctrl:1
	v_lshlrev_b32_e32 v74, 16, v59
	v_and_b32_e32 v75, 0xffff0000, v59
	v_add_f32_dpp v76, v76, v76 quad_perm:[2,3,0,1] row_mask:0xf bank_mask:0xf bound_ctrl:1
	v_lshlrev_b32_e32 v78, 16, v60
	v_and_b32_e32 v79, 0xffff0000, v60
	v_add_f32_dpp v76, v76, v76 row_half_mirror row_mask:0xf bank_mask:0xf bound_ctrl:1
	v_lshlrev_b32_e32 v80, 16, v61
	v_and_b32_e32 v81, 0xffff0000, v61
	v_add_f32_dpp v76, v76, v76 row_ror:8 row_mask:0xf bank_mask:0xf bound_ctrl:1
	s_mov_b32 s6, 0x3a27c5ac
	v_mov_b32_e32 v77, s6
	v_fmac_f32_e32 v77, 0x3c800000, v76
	v_rsq_f32_e32 v77, v77
	s_nop 0
	v_mul_f32_e32 v62, v62, v77
	v_mul_f32_e32 v63, v63, v77
	v_mul_f32_e32 v64, v64, v77
	v_mul_f32_e32 v65, v65, v77
	v_mul_f32_e32 v62, v12, v62
	v_mul_f32_e32 v63, v13, v63
	v_mul_f32_e32 v64, v14, v64
	v_mul_f32_e32 v65, v15, v65
	v_pk_add_f32 v[62:63], v[16:17], v[62:63]
	v_pk_add_f32 v[64:65], v[18:19], v[64:65]
	v_fmac_f32_e32 v62, v68, v72
	v_fmac_f32_e32 v63, v68, v73
	v_fmac_f32_e32 v64, v68, v74
	v_fmac_f32_e32 v65, v68, v75
	v_pk_mul_f32 v[62:63], v[62:63], v[78:79]
	v_pk_mul_f32 v[64:65], v[64:65], v[80:81]
	v_cvt_pk_bf16_f32 v62, v62, v63
	v_cvt_pk_bf16_f32 v63, v64, v65
	s_lshl_b32 s6, s5, 11
	s_add_u32 s8, s92, s6
	s_addc_u32 s9, s93, 0
	s_add_u32 s8, s8, 0x1e00600
	s_addc_u32 s9, s9, 0
	global_store_dwordx2 v11, v[62:63], s[8:9]
	s_branch .Lro_loop
.Lro_last_a:
	s_waitcnt vmcnt(0)
	v_pk_add_f32 v[62:63], v[24:25], v[28:29]
	v_pk_add_f32 v[64:65], v[26:27], v[30:31]
	v_pk_add_f32 v[66:67], v[62:63], v[64:65]
	v_add_f32_e32 v66, v66, v67
	v_lshlrev_b32_e32 v68, 16, v34
	v_and_b32_e32 v69, 0xffff0000, v34
	v_add_f32_dpp v66, v66, v66 quad_perm:[1,0,3,2] row_mask:0xf bank_mask:0xf bound_ctrl:1
	v_lshlrev_b32_e32 v70, 16, v35
	v_and_b32_e32 v71, 0xffff0000, v35
	v_add_f32_dpp v66, v66, v66 quad_perm:[2,3,0,1] row_mask:0xf bank_mask:0xf bound_ctrl:1
	v_lshlrev_b32_e32 v72, 16, v36
	v_and_b32_e32 v73, 0xffff0000, v36
	v_add_f32_dpp v66, v66, v66 row_half_mirror row_mask:0xf bank_mask:0xf bound_ctrl:1
	v_lshlrev_b32_e32 v74, 16, v37
	v_and_b32_e32 v75, 0xffff0000, v37
	v_add_f32_dpp v66, v66, v66 row_ror:8 row_mask:0xf bank_mask:0xf bound_ctrl:1
	v_pk_add_f32 v[68:69], v[68:69], v[72:73]
	v_pk_add_f32 v[70:71], v[70:71], v[74:75]
	v_lshlrev_b32_e32 v72, 16, v32
	v_and_b32_e32 v73, 0xffff0000, v32
	v_lshlrev_b32_e32 v74, 16, v33
	v_and_b32_e32 v75, 0xffff0000, v33
	v_pk_mul_f32 v[68:69], v[68:69], v[72:73]
	v_pk_mul_f32 v[70:71], v[70:71], v[74:75]
	v_pk_mul_f32 v[68:69], v[20:21], v[68:69]
	v_pk_mul_f32 v[70:71], v[22:23], v[70:71]
	v_pk_add_f32 v[68:69], v[68:69], v[70:71]
	v_add_f32_e32 v68, v68, v69
	v_fmac_f32_e32 v62, 0xbc800000, v66
	v_fmac_f32_e32 v63, 0xbc800000, v66
	v_add_f32_dpp v68, v68, v68 quad_perm:[1,0,3,2] row_mask:0xf bank_mask:0xf bound_ctrl:1
	v_fmac_f32_e32 v64, 0xbc800000, v66
	v_fmac_f32_e32 v65, 0xbc800000, v66
	v_add_f32_dpp v68, v68, v68 quad_perm:[2,3,0,1] row_mask:0xf bank_mask:0xf bound_ctrl:1
	v_pk_mul_f32 v[76:77], v[62:63], v[62:63]
	v_pk_fma_f32 v[76:77], v[64:65], v[64:65], v[76:77]
	v_add_f32_dpp v68, v68, v68 row_half_mirror row_mask:0xf bank_mask:0xf bound_ctrl:1
	s_nop 0
	s_nop 0
	v_add_f32_dpp v68, v68, v68 row_ror:8 row_mask:0xf bank_mask:0xf bound_ctrl:1
	v_add_f32_e32 v76, v76, v77
	v_lshlrev_b32_e32 v72, 16, v38
	v_and_b32_e32 v73, 0xffff0000, v38
	v_add_f32_dpp v76, v76, v76 quad_perm:[1,0,3,2] row_mask:0xf bank_mask:0xf bound_ctrl:1
	v_lshlrev_b32_e32 v74, 16, v39
	v_and_b32_e32 v75, 0xffff0000, v39
	v_add_f32_dpp v76, v76, v76 quad_perm:[2,3,0,1] row_mask:0xf bank_mask:0xf bound_ctrl:1
	v_lshlrev_b32_e32 v78, 16, v40
	v_and_b32_e32 v79, 0xffff0000, v40
	v_add_f32_dpp v76, v76, v76 row_half_mirror row_mask:0xf bank_mask:0xf bound_ctrl:1
	v_lshlrev_b32_e32 v80, 16, v41
	v_and_b32_e32 v81, 0xffff0000, v41
	v_add_f32_dpp v76, v76, v76 row_ror:8 row_mask:0xf bank_mask:0xf bound_ctrl:1
	s_mov_b32 s6, 0x3a27c5ac
	v_mov_b32_e32 v77, s6
	v_fmac_f32_e32 v77, 0x3c800000, v76
	v_rsq_f32_e32 v77, v77
	s_nop 0
	v_mul_f32_e32 v62, v62, v77
	v_mul_f32_e32 v63, v63, v77
	v_mul_f32_e32 v64, v64, v77
	v_mul_f32_e32 v65, v65, v77
	v_mul_f32_e32 v62, v12, v62
	v_mul_f32_e32 v63, v13, v63
	v_mul_f32_e32 v64, v14, v64
	v_mul_f32_e32 v65, v15, v65
	v_pk_add_f32 v[62:63], v[16:17], v[62:63]
	v_pk_add_f32 v[64:65], v[18:19], v[64:65]
	v_fmac_f32_e32 v62, v68, v72
	v_fmac_f32_e32 v63, v68, v73
	v_fmac_f32_e32 v64, v68, v74
	v_fmac_f32_e32 v65, v68, v75
	v_pk_mul_f32 v[62:63], v[62:63], v[78:79]
	v_pk_mul_f32 v[64:65], v[64:65], v[80:81]
	v_cvt_pk_bf16_f32 v62, v62, v63
	v_cvt_pk_bf16_f32 v63, v64, v65
	s_lshl_b32 s6, s4, 11
	s_add_u32 s8, s92, s6
	s_addc_u32 s9, s93, 0
	s_add_u32 s8, s8, 0x1e00600
	s_addc_u32 s9, s9, 0
	global_store_dwordx2 v11, v[62:63], s[8:9]
	s_branch .Lro_done
.Lro_last_b:
	s_waitcnt vmcnt(0)
	v_pk_add_f32 v[62:63], v[44:45], v[48:49]
	v_pk_add_f32 v[64:65], v[46:47], v[50:51]
	v_pk_add_f32 v[66:67], v[62:63], v[64:65]
	v_add_f32_e32 v66, v66, v67
	v_lshlrev_b32_e32 v68, 16, v54
	v_and_b32_e32 v69, 0xffff0000, v54
	v_add_f32_dpp v66, v66, v66 quad_perm:[1,0,3,2] row_mask:0xf bank_mask:0xf bound_ctrl:1
	v_lshlrev_b32_e32 v70, 16, v55
	v_and_b32_e32 v71, 0xffff0000, v55
	v_add_f32_dpp v66, v66, v66 quad_perm:[2,3,0,1] row_mask:0xf bank_mask:0xf bound_ctrl:1
	v_lshlrev_b32_e32 v72, 16, v56
	v_and_b32_e32 v73, 0xffff0000, v56
	v_add_f32_dpp v66, v66, v66 row_half_mirror row_mask:0xf bank_mask:0xf bound_ctrl:1
	v_lshlrev_b32_e32 v74, 16, v57
	v_and_b32_e32 v75, 0xffff0000, v57
	v_add_f32_dpp v66, v66, v66 row_ror:8 row_mask:0xf bank_mask:0xf bound_ctrl:1
	v_pk_add_f32 v[68:69], v[68:69], v[72:73]
	v_pk_add_f32 v[70:71], v[70:71], v[74:75]
	v_lshlrev_b32_e32 v72, 16, v52
	v_and_b32_e32 v73, 0xffff0000, v52
	v_lshlrev_b32_e32 v74, 16, v53
	v_and_b32_e32 v75, 0xffff0000, v53
	v_pk_mul_f32 v[68:69], v[68:69], v[72:73]
	v_pk_mul_f32 v[70:71], v[70:71], v[74:75]
	v_pk_mul_f32 v[68:69], v[20:21], v[68:69]
	v_pk_mul_f32 v[70:71], v[22:23], v[70:71]
	v_pk_add_f32 v[68:69], v[68:69], v[70:71]
	v_add_f32_e32 v68, v68, v69
	v_fmac_f32_e32 v62, 0xbc800000, v66
	v_fmac_f32_e32 v63, 0xbc800000, v66
	v_add_f32_dpp v68, v68, v68 quad_perm:[1,0,3,2] row_mask:0xf bank_mask:0xf bound_ctrl:1
	v_fmac_f32_e32 v64, 0xbc800000, v66
	v_fmac_f32_e32 v65, 0xbc800000, v66
	v_add_f32_dpp v68, v68, v68 quad_perm:[2,3,0,1] row_mask:0xf bank_mask:0xf bound_ctrl:1
	v_pk_mul_f32 v[76:77], v[62:63], v[62:63]
	v_pk_fma_f32 v[76:77], v[64:65], v[64:65], v[76:77]
	v_add_f32_dpp v68, v68, v68 row_half_mirror row_mask:0xf bank_mask:0xf bound_ctrl:1
	s_nop 0
	s_nop 0
	v_add_f32_dpp v68, v68, v68 row_ror:8 row_mask:0xf bank_mask:0xf bound_ctrl:1
	v_add_f32_e32 v76, v76, v77
	v_lshlrev_b32_e32 v72, 16, v58
	v_and_b32_e32 v73, 0xffff0000, v58
	v_add_f32_dpp v76, v76, v76 quad_perm:[1,0,3,2] row_mask:0xf bank_mask:0xf bound_ctrl:1
	v_lshlrev_b32_e32 v74, 16, v59
	v_and_b32_e32 v75, 0xffff0000, v59
	v_add_f32_dpp v76, v76, v76 quad_perm:[2,3,0,1] row_mask:0xf bank_mask:0xf bound_ctrl:1
	v_lshlrev_b32_e32 v78, 16, v60
	v_and_b32_e32 v79, 0xffff0000, v60
	v_add_f32_dpp v76, v76, v76 row_half_mirror row_mask:0xf bank_mask:0xf bound_ctrl:1
	v_lshlrev_b32_e32 v80, 16, v61
	v_and_b32_e32 v81, 0xffff0000, v61
	v_add_f32_dpp v76, v76, v76 row_ror:8 row_mask:0xf bank_mask:0xf bound_ctrl:1
	s_mov_b32 s6, 0x3a27c5ac
	v_mov_b32_e32 v77, s6
	v_fmac_f32_e32 v77, 0x3c800000, v76
	v_rsq_f32_e32 v77, v77
	s_nop 0
	v_mul_f32_e32 v62, v62, v77
	v_mul_f32_e32 v63, v63, v77
	v_mul_f32_e32 v64, v64, v77
	v_mul_f32_e32 v65, v65, v77
	v_mul_f32_e32 v62, v12, v62
	v_mul_f32_e32 v63, v13, v63
	v_mul_f32_e32 v64, v14, v64
	v_mul_f32_e32 v65, v15, v65
	v_pk_add_f32 v[62:63], v[16:17], v[62:63]
	v_pk_add_f32 v[64:65], v[18:19], v[64:65]
	v_fmac_f32_e32 v62, v68, v72
	v_fmac_f32_e32 v63, v68, v73
	v_fmac_f32_e32 v64, v68, v74
	v_fmac_f32_e32 v65, v68, v75
	v_pk_mul_f32 v[62:63], v[62:63], v[78:79]
	v_pk_mul_f32 v[64:65], v[64:65], v[80:81]
	v_cvt_pk_bf16_f32 v62, v62, v63
	v_cvt_pk_bf16_f32 v63, v64, v65
	s_lshl_b32 s6, s5, 11
	s_add_u32 s8, s92, s6
	s_addc_u32 s9, s93, 0
	s_add_u32 s8, s8, 0x1e00600
	s_addc_u32 s9, s9, 0
	global_store_dwordx2 v11, v[62:63], s[8:9]
.Lro_done:
.LBB0_274:
	s_or_b64 exec, exec, s[24:25]
	s_mov_b64 s[24:25], 0
